# combo10 + dn_prep: workgroups owning a sample chunk-head process it first (de-phases the two halves of the grid)
# speedup vs baseline: 1.0103x; 1.0103x over previous
; #define LAS __attribute__((address_space(3)))
; __device__ __forceinline__ void dn_prep(const Params& p, LAS unsigned char* lds) {
;     const int tid = threadIdx.x, lane = tid & 63, wid = tid >> 6, fr = lane & 15, fq = lane >> 4;
;     LAS bf16_t* Qs = (LAS bf16_t*)(lds + L_QS); LAS bf16_t* Ks = (LAS bf16_t*)(lds + L_KS); LAS bf16_t* Kts = (LAS bf16_t*)(lds + L_KT); LAS bf16_t* Vts = (LAS bf16_t*)(lds + L_VT);
;     LAS float* As = (LAS float*)(lds + L_AS); LAS bf16_t* Tu = (LAS bf16_t*)(lds + L_TU); LAS bf16_t* Tw = (LAS bf16_t*)(lds + L_TW);
;     LAS float* beta_s = (LAS float*)(lds + L_BG); LAS float* G_s = beta_s + 64;
;     const bf16_t* Z = (const bf16_t*)(p.ws + WS_Z);
;     const float* BA = (const float*)(p.ws + WS_BA);
;     unsigned char* dn = (unsigned char*)p.out;
;     LAS float* cw_s = (LAS float*)(lds + 108032);
;     int hb = -1;
;     for (int ci = blockIdx.x; ci < NCH; ci += gridDim.x) {
;     ...
;             for (int i = 1; i < 64; ++i) {
; #pragma unroll
;                 for (int j4 = 8; j4 < (i + 3) / 4; ++j4) rhi[j4 - 8] = *(const LAS f32x4*)(Asz + i * 68 + j4 * 4);
;                 if (i + 1 < 64) {
; #pragma unroll
;                     for (int j4 = 0; j4 < ((i + 4) / 4 < 8 ? (i + 4) / 4 : 8); ++j4) rlo[(i + 1) & 1][j4] = *(const LAS f32x4*)(Asz + (i + 1) * 68 + j4 * 4);
;                 }
;                 float a0 = (lane == i) ? 1.f : 0.f, a1 = 0.f, a2 = 0.f, a3 = 0.f;
.LBB0_187:
	s_cmp_lt_i32 s84, 3
	s_cselect_b64 s[4:5], -1, 0
	s_and_b64 s[0:1], s[4:5], s[2:3]
	s_andn2_b64 vcc, exec, s[0:1]
	s_cbranch_vccnz .LBB0_385
	s_cmpk_gt_i32 s33, 0x47f
	s_cbranch_scc1 .LBB0_385
	v_and_b32_e32 v152, 63, v184
	v_cmp_eq_u32_e32 vcc, 1, v152
	s_add_u32 s0, s50, 0xbc40000
	v_writelane_b32 v248, s4, 6
	v_cndmask_b32_e64 v160, 0, 1.0, vcc
	v_cmp_eq_u32_e32 vcc, 2, v152
	s_addc_u32 s1, s51, 0
	v_writelane_b32 v248, s5, 7
	v_cndmask_b32_e64 v161, 0, 1.0, vcc
	v_cmp_eq_u32_e32 vcc, 3, v152
	s_add_u32 s14, s48, 0x1200000
	v_writelane_b32 v248, s0, 8
	v_cndmask_b32_e64 v162, 0, 1.0, vcc
	v_cmp_eq_u32_e32 vcc, 4, v152
	s_addc_u32 s34, s49, 0
	v_writelane_b32 v248, s1, 9
	v_cndmask_b32_e64 v163, 0, 1.0, vcc
	v_cmp_eq_u32_e32 vcc, 5, v152
	s_add_u32 s0, s48, 0x2400000
	v_writelane_b32 v248, s0, 10
	v_cndmask_b32_e64 v164, 0, 1.0, vcc
	v_cmp_eq_u32_e32 vcc, 6, v152
	s_addc_u32 s0, s49, 0
	s_add_u32 s39, s48, 0x3600000
	v_cndmask_b32_e64 v165, 0, 1.0, vcc
	v_cmp_eq_u32_e32 vcc, 7, v152
	v_writelane_b32 v248, s0, 11
	s_addc_u32 s36, s49, 0
	v_cndmask_b32_e64 v166, 0, 1.0, vcc
	v_cmp_eq_u32_e32 vcc, 8, v152
	s_add_i32 s0, 0, 0x1a400
	v_lshlrev_b32_e32 v0, 2, v152
	v_cndmask_b32_e64 v167, 0, 1.0, vcc
	v_cmp_eq_u32_e32 vcc, 9, v152
	v_add_u32_e32 v153, s0, v0
	s_movk_i32 s0, 0xff
	v_cndmask_b32_e64 v168, 0, 1.0, vcc
	v_cmp_eq_u32_e32 vcc, 10, v152
	v_cmp_lt_u32_e64 s[4:5], s0, v184
	v_cmp_eq_u32_e64 s[0:1], 0, v152
	v_cndmask_b32_e64 v169, 0, 1.0, vcc
	v_cmp_eq_u32_e32 vcc, 11, v152
	v_writelane_b32 v248, s0, 12
	v_lshrrev_b32_e32 v1, 6, v184
	v_cndmask_b32_e64 v170, 0, 1.0, vcc
	v_cmp_eq_u32_e32 vcc, 12, v152
	v_writelane_b32 v248, s1, 13
	v_cndmask_b32_e64 v157, 0, 1.0, s[0:1]
	v_cndmask_b32_e64 v171, 0, 1.0, vcc
	v_cmp_eq_u32_e32 vcc, 13, v152
	v_cmp_gt_u32_e64 s[0:1], 2, v152
	v_bfe_u32 v3, v184, 6, 2
	v_cndmask_b32_e64 v172, 0, 1.0, vcc
	v_cmp_eq_u32_e32 vcc, 14, v152
	v_writelane_b32 v248, s0, 14
	v_lshlrev_b32_e32 v156, 4, v1
	v_cndmask_b32_e64 v173, 0, 1.0, vcc
	v_cmp_eq_u32_e32 vcc, 15, v152
	v_writelane_b32 v248, s1, 15
	v_cmp_gt_u32_e64 s[0:1], 4, v152
	v_cndmask_b32_e64 v174, 0, 1.0, vcc
	v_cmp_eq_u32_e32 vcc, 16, v152
	v_writelane_b32 v248, s0, 16
	v_lshlrev_b32_e32 v158, 3, v1
	v_cndmask_b32_e64 v175, 0, 1.0, vcc
	v_cmp_eq_u32_e32 vcc, 17, v152
	v_writelane_b32 v248, s1, 17
	v_cmp_gt_u32_e64 s[0:1], 8, v152
	v_cndmask_b32_e64 v176, 0, 1.0, vcc
	v_cmp_eq_u32_e32 vcc, 18, v152
	v_writelane_b32 v248, s0, 18
	v_lshlrev_b32_e32 v4, 10, v1
	v_cndmask_b32_e64 v177, 0, 1.0, vcc
	v_cmp_eq_u32_e32 vcc, 19, v152
	v_writelane_b32 v248, s1, 19
	v_cmp_gt_u32_e64 s[0:1], 16, v152
	v_cndmask_b32_e64 v178, 0, 1.0, vcc
	v_cmp_eq_u32_e32 vcc, 20, v152
	v_writelane_b32 v248, s0, 20
	v_lshrrev_b32_e32 v1, 1, v184
	v_cndmask_b32_e64 v179, 0, 1.0, vcc
	v_cmp_eq_u32_e32 vcc, 21, v152
	v_writelane_b32 v248, s1, 21
	v_cmp_gt_u32_e64 s[0:1], 32, v152
	v_cndmask_b32_e64 v180, 0, 1.0, vcc
	v_cmp_eq_u32_e32 vcc, 22, v152
	v_writelane_b32 v248, s0, 22
	v_and_b32_e32 v132, 0x1c0, v1
	v_cndmask_b32_e64 v181, 0, 1.0, vcc
	v_cmp_eq_u32_e32 vcc, 23, v152
	v_mov_b32_e32 v133, 0
	v_lshrrev_b32_e32 v1, 4, v184
	v_cndmask_b32_e64 v182, 0, 1.0, vcc
	v_cmp_eq_u32_e32 vcc, 24, v152
	v_writelane_b32 v248, s1, 23
	v_cmp_ne_u32_e64 s[0:1], 0, v3
	v_cndmask_b32_e64 v183, 0, 1.0, vcc
	v_cmp_eq_u32_e32 vcc, 25, v152
	s_add_i32 s37, 0, 0x1a500
	v_and_b32_e32 v2, 4, v1
	v_cndmask_b32_e64 v185, 0, 1.0, vcc
	v_cmp_eq_u32_e32 vcc, 26, v152
	v_writelane_b32 v248, s0, 24
	v_mov_b32_e32 v1, v133
	v_cndmask_b32_e64 v186, 0, 1.0, vcc
	v_cmp_eq_u32_e32 vcc, 27, v152
	v_add_u32_e32 v154, s37, v0
	v_writelane_b32 v248, s1, 25
	v_cndmask_b32_e64 v187, 0, 1.0, vcc
	v_cmp_eq_u32_e32 vcc, 28, v152
	v_lshl_add_u64 v[0:1], s[50:51], 0, v[0:1]
	s_mov_b64 s[0:1], 0xd0e8800
	v_cndmask_b32_e64 v188, 0, 1.0, vcc
	v_cmp_eq_u32_e32 vcc, 29, v152
	v_lshl_add_u64 v[136:137], v[0:1], 0, s[0:1]
	v_lshl_add_u32 v0, v184, 2, 0
	v_cndmask_b32_e64 v189, 0, 1.0, vcc
	v_cmp_eq_u32_e32 vcc, 30, v152
	v_add_u32_e32 v224, 0x1a600, v0
	s_add_u32 s31, s50, 0xbee8800
	v_cndmask_b32_e64 v190, 0, 1.0, vcc
	v_cmp_eq_u32_e32 vcc, 31, v152
	v_mbcnt_lo_u32_b32 v0, -1, 0
	v_cmp_gt_u32_e64 s[2:3], 64, v184
	v_cndmask_b32_e64 v191, 0, 1.0, vcc
	v_cmp_eq_u32_e32 vcc, 32, v152
	s_mov_b32 s41, 0
	v_lshlrev_b32_e32 v155, 4, v3
	v_cndmask_b32_e64 v192, 0, 1.0, vcc
	v_cmp_eq_u32_e32 vcc, 33, v152
	v_lshl_add_u64 v[134:135], s[48:49], 0, v[132:133]
	v_and_b32_e32 v159, 0x7f, v184
	v_cndmask_b32_e64 v193, 0, 1.0, vcc
	v_cmp_eq_u32_e32 vcc, 34, v152
	v_cmp_lt_u32_e64 s[20:21], 1, v3
	v_cmp_eq_u32_e64 s[22:23], 3, v3
	v_cndmask_b32_e64 v194, 0, 1.0, vcc
	v_cmp_eq_u32_e32 vcc, 35, v152
	s_addc_u32 s35, s51, 0
	s_mov_b32 s15, -1
	v_cndmask_b32_e64 v195, 0, 1.0, vcc
	v_cmp_eq_u32_e32 vcc, 36, v152
	v_mov_b32_e32 v225, 0x3ecc95a3
	s_movk_i32 s38, 0x1a00
	v_cndmask_b32_e64 v196, 0, 1.0, vcc
	v_cmp_eq_u32_e32 vcc, 37, v152
	s_mov_b64 s[42:43], 0x3000a00
	s_mov_b32 s8, 0x3000000
	v_cndmask_b32_e64 v197, 0, 1.0, vcc
	v_cmp_eq_u32_e32 vcc, 38, v152
	s_movk_i32 s9, 0x1800
	s_movk_i32 s10, 0x110
	v_cndmask_b32_e64 v198, 0, 1.0, vcc
	v_cmp_eq_u32_e32 vcc, 39, v152
	s_mov_b32 s11, 0x800000
	s_mov_b64 s[46:47], 0x3000e00
	v_cndmask_b32_e64 v199, 0, 1.0, vcc
	v_cmp_eq_u32_e32 vcc, 40, v152
	s_mov_b64 s[66:67], 0x3001200
	s_mov_b32 s12, 0x3001000
	v_cndmask_b32_e64 v200, 0, 1.0, vcc
	v_cmp_eq_u32_e32 vcc, 41, v152
	s_add_i32 s13, 0, 0x11800
	v_lshlrev_b32_e32 v226, 1, v4
	v_cndmask_b32_e64 v201, 0, 1.0, vcc
	v_cmp_eq_u32_e32 vcc, 42, v152
	v_lshlrev_b32_e32 v138, 1, v2
	v_mov_b32_e32 v140, 0x3f317218
	v_cndmask_b32_e64 v202, 0, 1.0, vcc
	v_cmp_eq_u32_e32 vcc, 43, v152
	v_mov_b32_e32 v227, 0x7f800000
	v_mov_b32_e32 v228, 0x7fc00000
	v_cndmask_b32_e64 v203, 0, 1.0, vcc
	v_cmp_eq_u32_e32 vcc, 44, v152
	v_mov_b32_e32 v229, 0xff800000
	v_mbcnt_hi_u32_b32 v230, -1, v0
	v_cndmask_b32_e64 v204, 0, 1.0, vcc
	v_cmp_eq_u32_e32 vcc, 45, v152
	s_mov_b32 s30, s33
	s_cmpk_lt_i32 s33, 0x80
	s_cbranch_scc0 .Ldn_ord0
	s_addk_i32 s30, 0x400
; #define LAS __attribute__((address_space(3)))
; __device__ __forceinline__ void dn_prep(const Params& p, LAS unsigned char* lds) {
;     ...
;     for (int ci = blockIdx.x; ci < NCH; ci += gridDim.x) {
;         const bool samp = ci >= 1024;
;         if ((ci & 3) != hb) { hb = ci & 3;
;     ...
;             for (int i = 1; i < 64; ++i) {
; #pragma unroll
;                 for (int j4 = 8; j4 < (i + 3) / 4; ++j4) rhi[j4 - 8] = *(const LAS f32x4*)(Asz + i * 68 + j4 * 4);
;                 if (i + 1 < 64) {
; #pragma unroll
;                     for (int j4 = 0; j4 < ((i + 4) / 4 < 8 ? (i + 4) / 4 : 8); ++j4) rlo[(i + 1) & 1][j4] = *(const LAS f32x4*)(Asz + (i + 1) * 68 + j4 * 4);
;                 }
;                 float a0 = (lane == i) ? 1.f : 0.f, a1 = 0.f, a2 = 0.f, a3 = 0.f;
.Ldn_ord0:
	s_nop 0
	v_cndmask_b32_e64 v205, 0, 1.0, vcc
	v_cmp_eq_u32_e32 vcc, 46, v152
	s_nop 1
	v_cndmask_b32_e64 v206, 0, 1.0, vcc
	v_cmp_eq_u32_e32 vcc, 47, v152
	s_nop 1
	v_cndmask_b32_e64 v207, 0, 1.0, vcc
	v_cmp_eq_u32_e32 vcc, 48, v152
	s_nop 1
	v_cndmask_b32_e64 v208, 0, 1.0, vcc
	v_cmp_eq_u32_e32 vcc, 49, v152
	s_nop 1
	v_cndmask_b32_e64 v209, 0, 1.0, vcc
	v_cmp_eq_u32_e32 vcc, 50, v152
	s_nop 1
	v_cndmask_b32_e64 v210, 0, 1.0, vcc
	v_cmp_eq_u32_e32 vcc, 51, v152
	s_nop 1
	v_cndmask_b32_e64 v211, 0, 1.0, vcc
	v_cmp_eq_u32_e32 vcc, 52, v152
	s_nop 1
	v_cndmask_b32_e64 v212, 0, 1.0, vcc
	v_cmp_eq_u32_e32 vcc, 53, v152
	s_nop 1
	v_cndmask_b32_e64 v213, 0, 1.0, vcc
	v_cmp_eq_u32_e32 vcc, 54, v152
	s_nop 1
	v_cndmask_b32_e64 v214, 0, 1.0, vcc
	v_cmp_eq_u32_e32 vcc, 55, v152
	s_nop 1
	v_cndmask_b32_e64 v215, 0, 1.0, vcc
	v_cmp_eq_u32_e32 vcc, 56, v152
	s_nop 1
	v_cndmask_b32_e64 v216, 0, 1.0, vcc
	v_cmp_eq_u32_e32 vcc, 57, v152
	s_nop 1
	v_cndmask_b32_e64 v217, 0, 1.0, vcc
	v_cmp_eq_u32_e32 vcc, 58, v152
	s_nop 1
	v_cndmask_b32_e64 v218, 0, 1.0, vcc
	v_cmp_eq_u32_e32 vcc, 59, v152
	s_nop 1
	v_cndmask_b32_e64 v219, 0, 1.0, vcc
	v_cmp_eq_u32_e32 vcc, 60, v152
	s_nop 1
	v_cndmask_b32_e64 v220, 0, 1.0, vcc
	v_cmp_eq_u32_e32 vcc, 61, v152
	s_nop 1
	v_cndmask_b32_e64 v221, 0, 1.0, vcc
	v_cmp_eq_u32_e32 vcc, 62, v152
	s_nop 1
	v_cndmask_b32_e64 v222, 0, 1.0, vcc
	v_cmp_eq_u32_e32 vcc, 63, v152
	s_nop 1
	v_cndmask_b32_e64 v223, 0, 1.0, vcc
	s_branch .LBB0_191
.LBB0_190:
	s_or_b64 exec, exec, s[26:27]
	s_waitcnt lgkmcnt(0)
	s_barrier
	s_cmpk_lt_i32 s30, 0x400
	s_cbranch_scc1 .Ldn_ord1
	s_addk_i32 s30, 0xfc00
	s_branch .Ldn_ord2
.Ldn_ord1:
	s_add_i32 s30, s30, s86
	s_cmpk_gt_i32 s30, 0x3ff
	s_cbranch_scc1 .LBB0_384
.Ldn_ord2:
.LBB0_191:
	s_and_b32 s17, s30, 3
	s_cmp_eq_u32 s17, s15
	s_cbranch_scc1 .LBB0_195
	s_waitcnt lgkmcnt(0)
	s_barrier
	v_lshl_or_b32 v0, s17, 7, v159
	s_mov_b64 s[0:1], 0
	v_mov_b32_e32 v1, v224
	v_mov_b32_e32 v2, v184
